# v28 without the unused row-gain load for the W_ffn_down items (their rows are not scaled)
# baseline (speedup 1.0000x reference)
; template <int NB>
; __device__ __forceinline__ void p0_batch(int it0, int stride, int lane, const P0Ptrs& a) {
;     ...
;     for (int q = 0; q < NB; ++q) { const bool ok = it0 < NFAST / 4; d[q] = p0_desc(p0_super(ok ? it0 : 0, q), lane, a); if (!ok) d[q].dst = nullptr;
; #pragma unroll
;         for (int i = 0; i < 8; ++i) v[q][i] = __builtin_nontemporal_load((const f32x4*)(d[q].src + (size_t)i * d[q].nsrc));
;         const float* kp = d[q].ks ? d[q].ks : a.ffn_g;
;         s0[q] = *(const f32x4*)(kp); s1[q] = *(const f32x4*)(kp + 4); }
.Lcv_wad:
	s_barrier
	global_load_lds_dwordx4 v[100:101], off
	v_lshl_add_u64 v[100:101], v[112:113], 0, s[38:39]
	s_add_i32 m0, s78, 0x2000
	v_lshl_add_u64 v[136:137], s[28:29], 0, v[144:145]
	global_load_lds_dwordx4 v[100:101], off
	v_lshl_add_u64 v[100:101], v[136:137], 0, s[40:41]
	s_add_i32 m0, s78, 0x4000
	v_lshl_add_u64 v[134:135], s[28:29], 0, v[148:149]
	global_load_lds_dwordx4 v[100:101], off
	v_lshl_add_u64 v[100:101], v[134:135], 0, s[42:43]
	s_mov_b32 m0, s58
	global_load_lds_dwordx4 v[100:101], off
	v_lshl_add_u64 v[100:101], v[134:135], 0, s[44:45]
	s_mov_b32 m0, s77
	global_load_lds_dwordx4 v[100:101], off
	s_cmp_gt_u32 s87, 20
	s_cbranch_scc1 .Lcv_done
	s_cmp_gt_u32 s87, 19
	s_cbranch_scc1 .Lcv_inc
	s_lshl_b32 s98, s90, 4
	global_load_dwordx4 v[238:241], v79, s[88:89] nt
	global_load_dwordx4 v[242:245], v79, s[88:89] offset:64 nt
	s_cmp_gt_u32 s32, 6
	s_cbranch_scc1 .Lcv_nogain
	global_load_dword v237, v80, s[94:95]
.Lcv_nogain:
	s_add_u32 s88, s88, s98
	s_addc_u32 s89, s89, 0
	s_add_u32 s94, s94, 64
	s_addc_u32 s95, s95, 0
	s_and_b32 s98, s87, 3
	s_cmp_lg_u32 s98, 3
	s_cbranch_scc1 .Lcv_inc
	s_cmp_gt_u32 s87, 18
	s_cbranch_scc1 .Lcv_inc
	s_add_i32 s99, s32, 1
	s_movk_i32 s98, 0x78
	s_cmp_lt_u32 s99, 7
	s_cselect_b32 s98, 0x60, s98
	s_cmp_eq_u32 s99, 0
	s_cselect_b32 s98, 0x50, s98
	s_cselect_b32 s99, 0, 0x58
	s_load_dwordx2 s[88:89], s[100:101], s98
	s_cmp_eq_u32 s99, 0
	s_cbranch_scc0 .Lcv_s1b_s
	s_bfe_u32 s99, s2, 0x50003
	s_cmp_lt_u32 s99, 16
	s_cselect_b32 s99, 64, 0x48
